# MLA loop: LDS tile write and next-tile loads moved between the two segments of each body
# baseline (speedup 1.0000x reference)
.Lmla_nopv_A:
	s_waitcnt lgkmcnt(11)
	v_mfma_f32_32x32x16_bf16 v[64:79], v[48:51], v[80:83], v[32:47]
	s_waitcnt lgkmcnt(10)
	v_mfma_f32_32x32x16_bf16 v[48:63], v[122:125], v[80:83], v[32:47]
	s_waitcnt lgkmcnt(9)
	v_mfma_f32_32x32x16_bf16 v[64:79], v[118:121], v[84:87], v[64:79]
	s_waitcnt lgkmcnt(8)
	v_mfma_f32_32x32x16_bf16 v[48:63], v[126:129], v[84:87], v[48:63]
	s_waitcnt lgkmcnt(7)
	v_mfma_f32_32x32x16_bf16 v[64:79], v[130:133], v[88:91], v[64:79]
	s_waitcnt lgkmcnt(6)
	v_mfma_f32_32x32x16_bf16 v[48:63], v[138:141], v[88:91], v[48:63]
	s_waitcnt lgkmcnt(5)
	v_mfma_f32_32x32x16_bf16 v[64:79], v[134:137], v[92:95], v[64:79]
	s_waitcnt lgkmcnt(4)
	v_mfma_f32_32x32x16_bf16 v[48:63], v[142:145], v[92:95], v[48:63]
	s_waitcnt lgkmcnt(3)
	v_mfma_f32_32x32x16_bf16 v[64:79], v[146:149], v[96:99], v[64:79]
	ds_read_b128 v[202:205], v177 offset:26624
	ds_read_b128 v[206:209], v177 offset:26656
	ds_read_b128 v[218:221], v177 offset:31232
	ds_read_b128 v[222:225], v177 offset:31264
	ds_read_b128 v[210:213], v177 offset:26688
	ds_read_b128 v[214:217], v177 offset:26720
	ds_read_b128 v[226:229], v177 offset:31296
	ds_read_b128 v[230:233], v177 offset:31328
	s_waitcnt lgkmcnt(10)
	v_mfma_f32_32x32x16_bf16 v[48:63], v[194:197], v[96:99], v[48:63]
	s_waitcnt lgkmcnt(9)
	v_mfma_f32_32x32x16_bf16 v[64:79], v[178:181], v[100:103], v[64:79]
	s_waitcnt lgkmcnt(8)
	v_mfma_f32_32x32x16_bf16 v[48:63], v[198:201], v[100:103], v[48:63]
	s_setprio 0
	s_add_i32 s12, s28, 1
	s_cmp_ge_i32 s12, s22
	s_cbranch_scc1 .Lmla_nowrite_A
	s_and_b32 s12, s12, 1
	s_mul_i32 s13, s12, 0x3400
	v_add3_u32 v172, s13, v165, v166
	s_waitcnt vmcnt(0)
	ds_write_b128 v172, v[104:107]
	v_add3_u32 v172, s13, v167, v168
	ds_write_b128 v172, v[108:111]
	s_mulk_i32 s12, 0x2400
	v_add_u32_e32 v172, s12, v169
	v_add_u32_e32 v172, 0x6800, v172
	ds_write2_b64 v172, v[114:115], v[116:117] offset1:2
	s_add_i32 s12, s28, 2
	s_cmp_ge_i32 s12, s22
	s_cbranch_scc1 .Lmla_nowrite_A
	s_nop 1
	global_load_dwordx4 v[104:107], v[150:151], off
	global_load_dwordx4 v[108:111], v[154:155], off
	global_load_dwordx4 v[114:117], v[152:153], off
	v_lshl_add_u64 v[150:151], v[150:151], 0, s[26:27]
	v_lshl_add_u64 v[154:155], v[154:155], 0, s[26:27]
	v_lshl_add_u64 v[152:153], v[152:153], 0, s[30:31]
.Lmla_nowrite_A:
	s_nop 10
	v_max_f32_e32 v172, v64, v65
	v_max3_f32 v173, v66, v67, v49
	v_max3_f32 v172, v172, v48, v50
	v_max3_f32 v172, v172, v51, v68
	v_max3_f32 v173, v173, v70, v71
	v_max3_f32 v172, v172, v69, v52
	v_max3_f32 v173, v173, v54, v55
	s_nop 1
	v_max3_f32 v172, v172, v53, v72
	v_max3_f32 v173, v173, v74, v75
	v_max3_f32 v172, v172, v73, v56
	v_max3_f32 v173, v173, v58, v59
	v_max3_f32 v172, v172, v57, v76
	v_max3_f32 v173, v173, v78, v79
	v_max3_f32 v172, v172, v77, v60
	s_nop 1
	v_max3_f32 v173, v173, v62, v63
	v_max3_f32 v172, v172, v61, v173
	v_mov_b32_e32 v173, v172
	s_nop 1
	v_permlane32_swap_b32_e32 v172, v173
	v_max_f32_e32 v177, v172, v173
	v_cmp_lt_f32_e32 vcc, s14, v177
	s_cbranch_vccz .Lmla_norescale_A
	v_max_f32_e32 v172, s15, v177
	v_max_f32_e32 v173, 0xc2c80000, v172
	v_exp_f32_e64 v173, -v173
	v_add_f32_e32 v156, v156, v172
	v_sub_f32_e32 v48, v48, v172
	v_sub_f32_e32 v49, v49, v172
	s_nop 1
	v_sub_f32_e32 v50, v50, v172
	v_sub_f32_e32 v51, v51, v172
	v_sub_f32_e32 v52, v52, v172
	v_sub_f32_e32 v53, v53, v172
	v_sub_f32_e32 v54, v54, v172
	v_sub_f32_e32 v55, v55, v172
	v_sub_f32_e32 v56, v56, v172
	s_nop 1
	v_sub_f32_e32 v57, v57, v172
	v_sub_f32_e32 v58, v58, v172
	v_sub_f32_e32 v59, v59, v172
	v_sub_f32_e32 v60, v60, v172
	v_sub_f32_e32 v61, v61, v172
	v_sub_f32_e32 v62, v62, v172
	v_sub_f32_e32 v63, v63, v172
	s_nop 1
	v_sub_f32_e32 v64, v64, v172
	v_sub_f32_e32 v65, v65, v172
	v_sub_f32_e32 v66, v66, v172
	v_sub_f32_e32 v67, v67, v172
	v_sub_f32_e32 v68, v68, v172
	v_sub_f32_e32 v69, v69, v172
	v_sub_f32_e32 v70, v70, v172
	s_nop 1
	v_sub_f32_e32 v71, v71, v172
	v_sub_f32_e32 v72, v72, v172
	v_sub_f32_e32 v73, v73, v172
	v_sub_f32_e32 v74, v74, v172
	v_sub_f32_e32 v75, v75, v172
	v_sub_f32_e32 v76, v76, v172
	v_sub_f32_e32 v77, v77, v172
	s_nop 1
	v_sub_f32_e32 v78, v78, v172
	v_sub_f32_e32 v79, v79, v172
	v_mul_f32_e32 v0, v0, v173
	v_mul_f32_e32 v1, v1, v173
	v_mul_f32_e32 v2, v2, v173
	v_mul_f32_e32 v3, v3, v173
	v_mul_f32_e32 v4, v4, v173
	s_nop 1
	v_mul_f32_e32 v5, v5, v173
	v_mul_f32_e32 v6, v6, v173
	v_mul_f32_e32 v7, v7, v173
	v_mul_f32_e32 v8, v8, v173
	v_mul_f32_e32 v9, v9, v173
	v_mul_f32_e32 v10, v10, v173
	v_mul_f32_e32 v11, v11, v173
	s_nop 1
	v_mul_f32_e32 v12, v12, v173
	v_mul_f32_e32 v13, v13, v173
	v_mul_f32_e32 v14, v14, v173
	v_mul_f32_e32 v15, v15, v173
	v_mul_f32_e32 v16, v16, v173
	v_mul_f32_e32 v17, v17, v173
	v_mul_f32_e32 v18, v18, v173
	s_nop 1
	v_mul_f32_e32 v19, v19, v173
	v_mul_f32_e32 v20, v20, v173
	v_mul_f32_e32 v21, v21, v173
	v_mul_f32_e32 v22, v22, v173
	v_mul_f32_e32 v23, v23, v173
	v_mul_f32_e32 v24, v24, v173
	v_mul_f32_e32 v25, v25, v173
	s_nop 1
	v_mul_f32_e32 v26, v26, v173
	v_mul_f32_e32 v27, v27, v173
	v_mul_f32_e32 v28, v28, v173
	v_mul_f32_e32 v29, v29, v173
	v_mul_f32_e32 v30, v30, v173
	v_mul_f32_e32 v31, v31, v173
	v_mul_f32_e32 v157, v157, v173
	s_nop 1
	v_sub_f32_e32 v32, 0, v156
	v_mov_b32_e32 v33, v32
	v_mov_b32_e32 v34, v32
	v_mov_b32_e32 v35, v32
	v_mov_b32_e32 v36, v32
	v_mov_b32_e32 v37, v32
	v_mov_b32_e32 v38, v32
	s_nop 1
	v_mov_b32_e32 v39, v32
	v_mov_b32_e32 v40, v32
	v_mov_b32_e32 v41, v32
	v_mov_b32_e32 v42, v32
	v_mov_b32_e32 v43, v32
	v_mov_b32_e32 v44, v32
	v_mov_b32_e32 v45, v32
	s_nop 1
	v_mov_b32_e32 v46, v32
	v_mov_b32_e32 v47, v32
.Lmla_norescale_A:
	v_exp_f32_e32 v64, v64
	v_exp_f32_e32 v65, v65
	v_exp_f32_e32 v66, v66
	v_exp_f32_e32 v67, v67
	s_nop 1
	v_exp_f32_e32 v68, v68
	v_exp_f32_e32 v69, v69
	v_exp_f32_e32 v70, v70
	v_exp_f32_e32 v71, v71
	s_nop 1
	v_cvt_pk_bf16_f32 v234, v64, v65
	v_cvt_pk_bf16_f32 v235, v66, v67
	v_cvt_pk_bf16_f32 v236, v68, v69
	v_cvt_pk_bf16_f32 v237, v70, v71
	v_exp_f32_e32 v72, v72
	v_exp_f32_e32 v73, v73
	s_nop 1
	v_exp_f32_e32 v74, v74
	v_exp_f32_e32 v75, v75
	v_exp_f32_e32 v76, v76
	v_exp_f32_e32 v77, v77
	s_nop 1
	v_exp_f32_e32 v78, v78
	v_exp_f32_e32 v79, v79
	v_cvt_pk_bf16_f32 v238, v72, v73
	v_cvt_pk_bf16_f32 v239, v74, v75
	v_cvt_pk_bf16_f32 v240, v76, v77
	s_nop 1
	v_cvt_pk_bf16_f32 v241, v78, v79
	v_exp_f32_e32 v48, v48
	v_exp_f32_e32 v49, v49
	v_exp_f32_e32 v50, v50
	s_nop 1
	v_exp_f32_e32 v51, v51
	v_exp_f32_e32 v52, v52
	v_exp_f32_e32 v53, v53
	v_exp_f32_e32 v54, v54
	s_nop 1
	v_exp_f32_e32 v55, v55
	v_cvt_pk_bf16_f32 v242, v48, v49
	v_cvt_pk_bf16_f32 v243, v50, v51
	v_cvt_pk_bf16_f32 v244, v52, v53
	v_cvt_pk_bf16_f32 v245, v54, v55
	v_exp_f32_e32 v56, v56
	s_nop 1
	v_exp_f32_e32 v57, v57
	v_exp_f32_e32 v58, v58
	v_exp_f32_e32 v59, v59
	v_exp_f32_e32 v60, v60
	s_nop 1
	v_exp_f32_e32 v61, v61
	v_exp_f32_e32 v62, v62
	v_exp_f32_e32 v63, v63
	v_cvt_pk_bf16_f32 v246, v56, v57
	s_nop 1
	v_cvt_pk_bf16_f32 v247, v58, v59
	v_cvt_pk_bf16_f32 v248, v60, v61
	v_cvt_pk_bf16_f32 v249, v62, v63
	v_add_f32_e32 v172, v64, v65
	v_add_f32_e32 v173, v66, v67
	v_add_f32_e32 v177, v68, v69
	v_add_f32_e32 v64, v70, v71
	s_nop 1
	v_add_f32_e32 v172, v172, v72
	v_add_f32_e32 v173, v173, v73
	v_add_f32_e32 v177, v177, v74
	v_add_f32_e32 v64, v64, v75
	v_add_f32_e32 v172, v172, v76
	v_add_f32_e32 v173, v173, v77
	v_add_f32_e32 v177, v177, v78
	s_nop 1
	v_add_f32_e32 v64, v64, v79
	v_add_f32_e32 v172, v172, v48
	v_add_f32_e32 v173, v173, v49
	v_add_f32_e32 v177, v177, v50
	v_add_f32_e32 v64, v64, v51
	v_add_f32_e32 v172, v172, v52
	v_add_f32_e32 v173, v173, v53
	s_nop 1
	v_add_f32_e32 v177, v177, v54
	v_add_f32_e32 v64, v64, v55
	v_add_f32_e32 v172, v172, v56
	v_add_f32_e32 v173, v173, v57
	v_add_f32_e32 v177, v177, v58
	v_add_f32_e32 v64, v64, v59
	v_add_f32_e32 v172, v172, v60
	s_nop 1
	v_add_f32_e32 v173, v173, v61
	v_add_f32_e32 v177, v177, v62
	v_add_f32_e32 v64, v64, v63
	v_add_f32_e32 v172, v172, v173
	v_add_f32_e32 v177, v177, v64
	v_add_f32_e32 v172, v172, v177
	v_add_f32_e32 v157, v157, v172
	s_nop 1
	s_mov_b32 s14, 0x41000000
	s_mov_b32 s15, 0
	s_waitcnt lgkmcnt(0)
	s_barrier
	s_add_i32 s28, s28, 1
	s_cmp_lt_i32 s28, s22
	s_cbranch_scc1 .Lmla_A_loop
	v_mfma_f32_32x32x16_bf16 v[16:31], v[202:205], v[234:237], v[16:31]
	v_mfma_f32_32x32x16_bf16 v[0:15], v[218:221], v[234:237], v[0:15]
	v_mfma_f32_32x32x16_bf16 v[16:31], v[206:209], v[238:241], v[16:31]
	v_mfma_f32_32x32x16_bf16 v[0:15], v[222:225], v[238:241], v[0:15]
	v_mfma_f32_32x32x16_bf16 v[16:31], v[210:213], v[242:245], v[16:31]
	v_mfma_f32_32x32x16_bf16 v[0:15], v[226:229], v[242:245], v[0:15]
	v_mfma_f32_32x32x16_bf16 v[16:31], v[214:217], v[246:249], v[16:31]
	v_mfma_f32_32x32x16_bf16 v[0:15], v[230:233], v[246:249], v[0:15]
	s_branch .Lmla_exit

.Lmla_norescale_B:
	v_exp_f32_e32 v64, v64
	v_exp_f32_e32 v65, v65
	v_exp_f32_e32 v66, v66
	v_exp_f32_e32 v67, v67
	v_exp_f32_e32 v68, v68
	v_exp_f32_e32 v69, v69
	v_exp_f32_e32 v70, v70
	v_exp_f32_e32 v71, v71
	v_cvt_pk_bf16_f32 v234, v64, v65
	v_cvt_pk_bf16_f32 v235, v66, v67
	v_cvt_pk_bf16_f32 v236, v68, v69
	v_cvt_pk_bf16_f32 v237, v70, v71
	v_exp_f32_e32 v72, v72
	v_exp_f32_e32 v73, v73
	v_exp_f32_e32 v74, v74
	v_exp_f32_e32 v75, v75
	v_exp_f32_e32 v76, v76
	v_exp_f32_e32 v77, v77
	v_exp_f32_e32 v78, v78
	v_exp_f32_e32 v79, v79
	v_cvt_pk_bf16_f32 v238, v72, v73
	v_cvt_pk_bf16_f32 v239, v74, v75
	v_cvt_pk_bf16_f32 v240, v76, v77
	v_cvt_pk_bf16_f32 v241, v78, v79
	v_exp_f32_e32 v48, v48
	v_exp_f32_e32 v49, v49
	v_exp_f32_e32 v50, v50
	v_exp_f32_e32 v51, v51
	v_exp_f32_e32 v52, v52
	v_exp_f32_e32 v53, v53
	v_exp_f32_e32 v54, v54
	v_exp_f32_e32 v55, v55
	v_cvt_pk_bf16_f32 v242, v48, v49
	v_cvt_pk_bf16_f32 v243, v50, v51
	v_cvt_pk_bf16_f32 v244, v52, v53
	v_cvt_pk_bf16_f32 v245, v54, v55
	v_exp_f32_e32 v56, v56
	v_exp_f32_e32 v57, v57
	v_exp_f32_e32 v58, v58
	v_exp_f32_e32 v59, v59
	v_exp_f32_e32 v60, v60
	v_exp_f32_e32 v61, v61
	v_exp_f32_e32 v62, v62
	v_exp_f32_e32 v63, v63
	v_cvt_pk_bf16_f32 v246, v56, v57
	v_cvt_pk_bf16_f32 v247, v58, v59
	v_cvt_pk_bf16_f32 v248, v60, v61
	v_cvt_pk_bf16_f32 v249, v62, v63
	v_add_f32_e32 v172, v64, v65
	v_add_f32_e32 v173, v66, v67
	v_add_f32_e32 v177, v68, v69
	v_add_f32_e32 v64, v70, v71
	v_add_f32_e32 v172, v172, v72
	v_add_f32_e32 v173, v173, v73
	v_add_f32_e32 v177, v177, v74
	v_add_f32_e32 v64, v64, v75
	v_add_f32_e32 v172, v172, v76
	v_add_f32_e32 v173, v173, v77
	v_add_f32_e32 v177, v177, v78
	v_add_f32_e32 v64, v64, v79
	v_add_f32_e32 v172, v172, v48
	v_add_f32_e32 v173, v173, v49
	v_add_f32_e32 v177, v177, v50
	v_add_f32_e32 v64, v64, v51
	v_add_f32_e32 v172, v172, v52
	v_add_f32_e32 v173, v173, v53
	v_add_f32_e32 v177, v177, v54
	v_add_f32_e32 v64, v64, v55
	v_add_f32_e32 v172, v172, v56
	v_add_f32_e32 v173, v173, v57
	v_add_f32_e32 v177, v177, v58
	v_add_f32_e32 v64, v64, v59
	v_add_f32_e32 v172, v172, v60
	v_add_f32_e32 v173, v173, v61
	v_add_f32_e32 v177, v177, v62
	v_add_f32_e32 v64, v64, v63
	v_add_f32_e32 v172, v172, v173
	v_add_f32_e32 v177, v177, v64
	v_add_f32_e32 v172, v172, v177
	v_add_f32_e32 v157, v157, v172
	s_mov_b32 s14, 0x41000000
	s_mov_b32 s15, 0
	s_add_i32 s12, s28, 1
	s_cmp_ge_i32 s12, s22
	s_cbranch_scc1 .Lmla_nowrite_B
	s_and_b32 s12, s12, 1
	s_mul_i32 s13, s12, 0x3400
	v_add3_u32 v172, s13, v165, v166
	s_waitcnt vmcnt(0)
	ds_write_b128 v172, v[104:107]
	s_mulk_i32 s12, 0x2400
	v_add_u32_e32 v172, s12, v169
	v_add_u32_e32 v172, 0x6800, v172
	ds_write2_b64 v172, v[114:115], v[116:117] offset1:2
	s_add_i32 s12, s28, 2
	s_cmp_ge_i32 s12, s22
	s_cbranch_scc1 .Lmla_nowrite_B
	s_nop 1
	global_load_dwordx4 v[104:107], v[150:151], off
	global_load_dwordx4 v[114:117], v[152:153], off
	v_lshl_add_u64 v[150:151], v[150:151], 0, s[26:27]
	v_lshl_add_u64 v[152:153], v[152:153], 0, s[30:31]
.Lmla_nowrite_B:
	s_and_b32 s12, s28, 1
	s_mul_i32 s13, s12, 0x3400
	v_add_u32_e32 v52, s13, v112
	ds_read_b128 v[48:51], v52
	ds_read_b128 v[122:125], v52 offset:6656
	ds_read_b128 v[118:121], v52 offset:32
	ds_read_b128 v[126:129], v52 offset:6688
	ds_read_b128 v[130:133], v52 offset:64
	ds_read_b128 v[138:141], v52 offset:6720
	ds_read_b128 v[134:137], v52 offset:96
	ds_read_b128 v[142:145], v52 offset:6752
	ds_read_b128 v[146:149], v52 offset:128
	ds_read_b128 v[194:197], v52 offset:6784
	ds_read_b128 v[178:181], v52 offset:160
	ds_read_b128 v[198:201], v52 offset:6816
	s_mul_i32 s13, s12, 0x2400
	v_add_u32_e32 v177, s13, v176
	s_setprio 3
	v_mfma_f32_32x32x16_bf16 v[16:31], v[202:205], v[234:237], v[16:31]
	v_mfma_f32_32x32x16_bf16 v[0:15], v[218:221], v[234:237], v[0:15]
	v_mfma_f32_32x32x16_bf16 v[16:31], v[206:209], v[238:241], v[16:31]
	v_mfma_f32_32x32x16_bf16 v[0:15], v[222:225], v[238:241], v[0:15]
	v_mfma_f32_32x32x16_bf16 v[16:31], v[210:213], v[242:245], v[16:31]
	v_mfma_f32_32x32x16_bf16 v[0:15], v[226:229], v[242:245], v[0:15]
	v_mfma_f32_32x32x16_bf16 v[16:31], v[214:217], v[246:249], v[16:31]
	v_mfma_f32_32x32x16_bf16 v[0:15], v[230:233], v[246:249], v[0:15]
	s_waitcnt lgkmcnt(11)
	v_mfma_f32_32x32x16_bf16 v[64:79], v[48:51], v[80:83], v[32:47]
	s_waitcnt lgkmcnt(10)
	v_mfma_f32_32x32x16_bf16 v[48:63], v[122:125], v[80:83], v[32:47]
	s_waitcnt lgkmcnt(9)
	v_mfma_f32_32x32x16_bf16 v[64:79], v[118:121], v[84:87], v[64:79]
	s_waitcnt lgkmcnt(8)
	v_mfma_f32_32x32x16_bf16 v[48:63], v[126:129], v[84:87], v[48:63]
	s_waitcnt lgkmcnt(7)
	v_mfma_f32_32x32x16_bf16 v[64:79], v[130:133], v[88:91], v[64:79]
	s_waitcnt lgkmcnt(6)
	v_mfma_f32_32x32x16_bf16 v[48:63], v[138:141], v[88:91], v[48:63]
	s_waitcnt lgkmcnt(5)
	v_mfma_f32_32x32x16_bf16 v[64:79], v[134:137], v[92:95], v[64:79]
	s_waitcnt lgkmcnt(4)
	v_mfma_f32_32x32x16_bf16 v[48:63], v[142:145], v[92:95], v[48:63]
	s_waitcnt lgkmcnt(3)
	v_mfma_f32_32x32x16_bf16 v[64:79], v[146:149], v[96:99], v[64:79]
	ds_read_b128 v[202:205], v177 offset:26624
	ds_read_b128 v[206:209], v177 offset:26656
	ds_read_b128 v[218:221], v177 offset:31232
	ds_read_b128 v[222:225], v177 offset:31264
	ds_read_b128 v[210:213], v177 offset:26688
	ds_read_b128 v[214:217], v177 offset:26720
	ds_read_b128 v[226:229], v177 offset:31296
	ds_read_b128 v[230:233], v177 offset:31328
	s_waitcnt lgkmcnt(10)
	v_mfma_f32_32x32x16_bf16 v[48:63], v[194:197], v[96:99], v[48:63]
	s_waitcnt lgkmcnt(9)
	v_mfma_f32_32x32x16_bf16 v[64:79], v[178:181], v[100:103], v[64:79]
	s_waitcnt lgkmcnt(8)
	v_mfma_f32_32x32x16_bf16 v[48:63], v[198:201], v[100:103], v[48:63]
	s_setprio 0
	s_waitcnt lgkmcnt(0)
	s_barrier
	s_add_i32 s28, s28, 1
	s_cmp_lt_i32 s28, s22
	s_cbranch_scc1 .Lmla_B_loop
